# PG epilogue: output rows stored with the default cache policy instead of nt
# speedup vs baseline: 1.0059x; 1.0059x over previous
; __global__ void __launch_bounds__(512, 2) mega(Params P0) {
;     ...
;         else if (ph == 11) { const float* r3 = (const float*)(ws + WS_RSS3); const float* fw = P.in[23]; const f32x4* h3 = (const f32x4*)(ws + WS_H1);
;             const int nchunk = NTOK * DM / 4 / 1024; const int wv = bid * 8 + (tid >> 6), lane = tid & 63;
;             for (int ck = wv; ck < nchunk; ck += G * 8) { f32x4 v[16];
; #pragma unroll
;                 for (int j = 0; j < 16; ++j) v[j] = __builtin_nontemporal_load(h3 + (ck * 16 + j) * 64 + lane);
; #pragma unroll
;                 for (int j = 0; j < 16; ++j) { const int i = (ck * 16 + j) * 64 + lane; const int row = i >> 8, c4 = i & 255; const float rstd = rsqrtf(r3[row] * (1.0f / DM) + 1e-6f);
;                     __builtin_nontemporal_store(v[j] * rstd * *(const f32x4*)(fw + 4 * c4), (f32x4*)P.out + i); } } }
.Lpg_met:
	s_or_b64 exec, exec, s[66:67]
	s_barrier
	s_barrier
	v_mov_b32_e32 v205, 0
	v_and_b32_e32 v229, 15, v203
	v_lshlrev_b32_e32 v229, 2, v229
	s_mov_b64 s[66:67], exec
	s_and_b64 exec, exec, s[42:43]
	global_atomic_add_f32 v164, v202, v205, s[36:37] sc0
	global_atomic_add_f32 v165, v202, v205, s[36:37] offset:64 sc0
	global_atomic_add_f32 v166, v202, v205, s[36:37] offset:128 sc0
	global_atomic_add_f32 v167, v202, v205, s[36:37] offset:192 sc0
	global_atomic_add_f32 v170, v202, v205, s[36:37] offset:512 sc0
	global_atomic_add_f32 v171, v202, v205, s[36:37] offset:576 sc0
	global_atomic_add_f32 v172, v202, v205, s[36:37] offset:640 sc0
	global_atomic_add_f32 v173, v202, v205, s[36:37] offset:704 sc0
	s_mov_b64 exec, s[66:67]
	global_load_dwordx4 v[240:243], v204, s[74:75]
	global_load_dwordx4 v[244:247], v204, s[74:75] offset:16
	global_load_dwordx4 v[248:251], v204, s[74:75] offset:512
	global_load_dwordx4 v[232:235], v204, s[74:75] offset:528
	s_waitcnt vmcnt(4)
	ds_bpermute_b32 v164, v229, v164
	ds_bpermute_b32 v165, v229, v165
	ds_bpermute_b32 v166, v229, v166
	ds_bpermute_b32 v167, v229, v167
	ds_bpermute_b32 v170, v229, v170
	ds_bpermute_b32 v171, v229, v171
	ds_bpermute_b32 v172, v229, v172
	ds_bpermute_b32 v173, v229, v173
	s_waitcnt lgkmcnt(0)
	v_fmamk_f32 v164, v164, 0x3a800000, v210
	v_fmamk_f32 v165, v165, 0x3a800000, v210
	v_fmamk_f32 v166, v166, 0x3a800000, v210
	v_fmamk_f32 v167, v167, 0x3a800000, v210
	v_fmamk_f32 v170, v170, 0x3a800000, v210
	v_fmamk_f32 v171, v171, 0x3a800000, v210
	v_fmamk_f32 v172, v172, 0x3a800000, v210
	v_fmamk_f32 v173, v173, 0x3a800000, v210
	v_mul_f32_e32 v130, 0x4b800000, v164
	v_mul_f32_e32 v131, 0x4b800000, v165
	v_mul_f32_e32 v132, 0x4b800000, v166
	v_mul_f32_e32 v133, 0x4b800000, v167
	v_mul_f32_e32 v134, 0x4b800000, v170
	v_mul_f32_e32 v135, 0x4b800000, v171
	v_mul_f32_e32 v136, 0x4b800000, v172
	v_mul_f32_e32 v137, 0x4b800000, v173
	v_cmp_gt_f32_e64 s[62:63], s30, v164
	v_cmp_gt_f32_e64 s[64:65], s30, v165
	v_cmp_gt_f32_e64 s[66:67], s30, v166
	v_cmp_gt_f32_e64 s[68:69], s30, v167
	s_nop 1
	v_cndmask_b32_e64 v164, v164, v130, s[62:63]
	v_cndmask_b32_e64 v165, v165, v131, s[64:65]
	v_cndmask_b32_e64 v166, v166, v132, s[66:67]
	v_cndmask_b32_e64 v167, v167, v133, s[68:69]
	v_rsq_f32_e32 v164, v164
	v_rsq_f32_e32 v165, v165
	v_rsq_f32_e32 v166, v166
	v_rsq_f32_e32 v167, v167
	s_nop 0
	v_mul_f32_e32 v130, 0x45800000, v164
	v_mul_f32_e32 v131, 0x45800000, v165
	v_mul_f32_e32 v132, 0x45800000, v166
	v_mul_f32_e32 v133, 0x45800000, v167
	v_cndmask_b32_e64 v164, v164, v130, s[62:63]
	v_cndmask_b32_e64 v165, v165, v131, s[64:65]
	v_cndmask_b32_e64 v166, v166, v132, s[66:67]
	v_cndmask_b32_e64 v167, v167, v133, s[68:69]
	v_cmp_gt_f32_e64 s[62:63], s30, v170
	v_cmp_gt_f32_e64 s[64:65], s30, v171
	v_cmp_gt_f32_e64 s[66:67], s30, v172
	v_cmp_gt_f32_e64 s[68:69], s30, v173
	s_nop 1
	v_cndmask_b32_e64 v170, v170, v134, s[62:63]
	v_cndmask_b32_e64 v171, v171, v135, s[64:65]
	v_cndmask_b32_e64 v172, v172, v136, s[66:67]
	v_cndmask_b32_e64 v173, v173, v137, s[68:69]
	v_rsq_f32_e32 v170, v170
	v_rsq_f32_e32 v171, v171
	v_rsq_f32_e32 v172, v172
	v_rsq_f32_e32 v173, v173
	s_nop 0
	v_mul_f32_e32 v134, 0x45800000, v170
	v_mul_f32_e32 v135, 0x45800000, v171
	v_mul_f32_e32 v136, 0x45800000, v172
	v_mul_f32_e32 v137, 0x45800000, v173
	v_cndmask_b32_e64 v170, v170, v134, s[62:63]
	v_cndmask_b32_e64 v171, v171, v135, s[64:65]
	v_cndmask_b32_e64 v172, v172, v136, s[66:67]
	v_cndmask_b32_e64 v173, v173, v137, s[68:69]
	s_waitcnt vmcnt(0)
	s_add_u32 s62, s52, 0x0
	s_addc_u32 s63, s53, 0
	v_pk_mul_f32 v[122:123], v[122:123], v[164:165] op_sel_hi:[1,0]
	v_pk_mul_f32 v[124:125], v[124:125], v[164:165] op_sel_hi:[1,0]
	v_pk_mul_f32 v[114:115], v[114:115], v[164:165] op_sel_hi:[1,0]
	v_pk_mul_f32 v[116:117], v[116:117], v[164:165] op_sel_hi:[1,0]
	v_pk_mul_f32 v[110:111], v[110:111], v[164:165] op_sel_hi:[1,0]
	v_pk_mul_f32 v[112:113], v[112:113], v[164:165] op_sel_hi:[1,0]
	v_pk_mul_f32 v[106:107], v[106:107], v[164:165] op_sel_hi:[1,0]
	v_pk_mul_f32 v[108:109], v[108:109], v[164:165] op_sel_hi:[1,0]
	v_pk_mul_f32 v[122:123], v[122:123], v[240:241]
	v_pk_mul_f32 v[124:125], v[124:125], v[242:243]
	v_pk_mul_f32 v[114:115], v[114:115], v[244:245]
	v_pk_mul_f32 v[116:117], v[116:117], v[246:247]
	v_pk_mul_f32 v[110:111], v[110:111], v[248:249]
	v_pk_mul_f32 v[112:113], v[112:113], v[250:251]
	v_pk_mul_f32 v[106:107], v[106:107], v[232:233]
	v_pk_mul_f32 v[108:109], v[108:109], v[234:235]
	global_store_dwordx4 v200, v[122:125], s[62:63]
	global_store_dwordx4 v200, v[114:117], s[62:63] offset:16
	global_store_dwordx4 v200, v[110:113], s[62:63] offset:512
	global_store_dwordx4 v200, v[106:109], s[62:63] offset:528
	s_add_u32 s62, s52, 0x10000
	s_addc_u32 s63, s53, 0
	v_pk_mul_f32 v[126:127], v[126:127], v[164:165] op_sel:[0,1] op_sel_hi:[1,1]
	v_pk_mul_f32 v[128:129], v[128:129], v[164:165] op_sel:[0,1] op_sel_hi:[1,1]
	v_pk_mul_f32 v[118:119], v[118:119], v[164:165] op_sel:[0,1] op_sel_hi:[1,1]
	v_pk_mul_f32 v[120:121], v[120:121], v[164:165] op_sel:[0,1] op_sel_hi:[1,1]
	v_pk_mul_f32 v[102:103], v[102:103], v[164:165] op_sel:[0,1] op_sel_hi:[1,1]
	v_pk_mul_f32 v[104:105], v[104:105], v[164:165] op_sel:[0,1] op_sel_hi:[1,1]
	v_pk_mul_f32 v[98:99], v[98:99], v[164:165] op_sel:[0,1] op_sel_hi:[1,1]
	v_pk_mul_f32 v[100:101], v[100:101], v[164:165] op_sel:[0,1] op_sel_hi:[1,1]
	v_pk_mul_f32 v[126:127], v[126:127], v[240:241]
	v_pk_mul_f32 v[128:129], v[128:129], v[242:243]
	v_pk_mul_f32 v[118:119], v[118:119], v[244:245]
	v_pk_mul_f32 v[120:121], v[120:121], v[246:247]
	v_pk_mul_f32 v[102:103], v[102:103], v[248:249]
; __global__ void __launch_bounds__(512, 2) mega(Params P0) {
;     ...
;         else if (ph == 11) { const float* r3 = (const float*)(ws + WS_RSS3); const float* fw = P.in[23]; const f32x4* h3 = (const f32x4*)(ws + WS_H1);
;             const int nchunk = NTOK * DM / 4 / 1024; const int wv = bid * 8 + (tid >> 6), lane = tid & 63;
;             for (int ck = wv; ck < nchunk; ck += G * 8) { f32x4 v[16];
; #pragma unroll
;                 for (int j = 0; j < 16; ++j) v[j] = __builtin_nontemporal_load(h3 + (ck * 16 + j) * 64 + lane);
; #pragma unroll
;                 for (int j = 0; j < 16; ++j) { const int i = (ck * 16 + j) * 64 + lane; const int row = i >> 8, c4 = i & 255; const float rstd = rsqrtf(r3[row] * (1.0f / DM) + 1e-6f);
;                     __builtin_nontemporal_store(v[j] * rstd * *(const f32x4*)(fw + 4 * c4), (f32x4*)P.out + i); } } }
	v_pk_mul_f32 v[104:105], v[104:105], v[250:251]
	v_pk_mul_f32 v[98:99], v[98:99], v[232:233]
	v_pk_mul_f32 v[100:101], v[100:101], v[234:235]
	global_store_dwordx4 v200, v[126:129], s[62:63]
	global_store_dwordx4 v200, v[118:121], s[62:63] offset:16
	global_store_dwordx4 v200, v[102:105], s[62:63] offset:512
	global_store_dwordx4 v200, v[98:101], s[62:63] offset:528
	s_add_u32 s62, s52, 0x20000
	s_addc_u32 s63, s53, 0
	v_pk_mul_f32 v[94:95], v[94:95], v[166:167] op_sel_hi:[1,0]
	v_pk_mul_f32 v[96:97], v[96:97], v[166:167] op_sel_hi:[1,0]
	v_pk_mul_f32 v[90:91], v[90:91], v[166:167] op_sel_hi:[1,0]
	v_pk_mul_f32 v[92:93], v[92:93], v[166:167] op_sel_hi:[1,0]
	v_pk_mul_f32 v[86:87], v[86:87], v[166:167] op_sel_hi:[1,0]
	v_pk_mul_f32 v[88:89], v[88:89], v[166:167] op_sel_hi:[1,0]
	v_pk_mul_f32 v[82:83], v[82:83], v[166:167] op_sel_hi:[1,0]
	v_pk_mul_f32 v[84:85], v[84:85], v[166:167] op_sel_hi:[1,0]
	v_pk_mul_f32 v[94:95], v[94:95], v[240:241]
	v_pk_mul_f32 v[96:97], v[96:97], v[242:243]
	v_pk_mul_f32 v[90:91], v[90:91], v[244:245]
	v_pk_mul_f32 v[92:93], v[92:93], v[246:247]
	v_pk_mul_f32 v[86:87], v[86:87], v[248:249]
	v_pk_mul_f32 v[88:89], v[88:89], v[250:251]
	v_pk_mul_f32 v[82:83], v[82:83], v[232:233]
	v_pk_mul_f32 v[84:85], v[84:85], v[234:235]
	global_store_dwordx4 v200, v[94:97], s[62:63]
	global_store_dwordx4 v200, v[90:93], s[62:63] offset:16
	global_store_dwordx4 v200, v[86:89], s[62:63] offset:512
	global_store_dwordx4 v200, v[82:85], s[62:63] offset:528
	s_add_u32 s62, s52, 0x30000
	s_addc_u32 s63, s53, 0
	v_pk_mul_f32 v[78:79], v[78:79], v[166:167] op_sel:[0,1] op_sel_hi:[1,1]
	v_pk_mul_f32 v[80:81], v[80:81], v[166:167] op_sel:[0,1] op_sel_hi:[1,1]
	v_pk_mul_f32 v[74:75], v[74:75], v[166:167] op_sel:[0,1] op_sel_hi:[1,1]
	v_pk_mul_f32 v[76:77], v[76:77], v[166:167] op_sel:[0,1] op_sel_hi:[1,1]
	v_pk_mul_f32 v[70:71], v[70:71], v[166:167] op_sel:[0,1] op_sel_hi:[1,1]
	v_pk_mul_f32 v[72:73], v[72:73], v[166:167] op_sel:[0,1] op_sel_hi:[1,1]
	v_pk_mul_f32 v[66:67], v[66:67], v[166:167] op_sel:[0,1] op_sel_hi:[1,1]
	v_pk_mul_f32 v[68:69], v[68:69], v[166:167] op_sel:[0,1] op_sel_hi:[1,1]
	v_pk_mul_f32 v[78:79], v[78:79], v[240:241]
	v_pk_mul_f32 v[80:81], v[80:81], v[242:243]
	v_pk_mul_f32 v[74:75], v[74:75], v[244:245]
	v_pk_mul_f32 v[76:77], v[76:77], v[246:247]
	v_pk_mul_f32 v[70:71], v[70:71], v[248:249]
	v_pk_mul_f32 v[72:73], v[72:73], v[250:251]
	v_pk_mul_f32 v[66:67], v[66:67], v[232:233]
	v_pk_mul_f32 v[68:69], v[68:69], v[234:235]
	global_store_dwordx4 v200, v[78:81], s[62:63]
	global_store_dwordx4 v200, v[74:77], s[62:63] offset:16
	global_store_dwordx4 v200, v[70:73], s[62:63] offset:512
	global_store_dwordx4 v200, v[66:69], s[62:63] offset:528
	s_add_u32 s62, s52, 0x80000
	s_addc_u32 s63, s53, 0
	v_pk_mul_f32 v[62:63], v[62:63], v[170:171] op_sel_hi:[1,0]
	v_pk_mul_f32 v[64:65], v[64:65], v[170:171] op_sel_hi:[1,0]
	v_pk_mul_f32 v[58:59], v[58:59], v[170:171] op_sel_hi:[1,0]
	v_pk_mul_f32 v[60:61], v[60:61], v[170:171] op_sel_hi:[1,0]
	v_pk_mul_f32 v[54:55], v[54:55], v[170:171] op_sel_hi:[1,0]
	v_pk_mul_f32 v[56:57], v[56:57], v[170:171] op_sel_hi:[1,0]
	v_pk_mul_f32 v[50:51], v[50:51], v[170:171] op_sel_hi:[1,0]
	v_pk_mul_f32 v[52:53], v[52:53], v[170:171] op_sel_hi:[1,0]
	v_pk_mul_f32 v[62:63], v[62:63], v[240:241]
	v_pk_mul_f32 v[64:65], v[64:65], v[242:243]
	v_pk_mul_f32 v[58:59], v[58:59], v[244:245]
	v_pk_mul_f32 v[60:61], v[60:61], v[246:247]
	v_pk_mul_f32 v[54:55], v[54:55], v[248:249]
	v_pk_mul_f32 v[56:57], v[56:57], v[250:251]
	v_pk_mul_f32 v[50:51], v[50:51], v[232:233]
	v_pk_mul_f32 v[52:53], v[52:53], v[234:235]
	global_store_dwordx4 v200, v[62:65], s[62:63]
	global_store_dwordx4 v200, v[58:61], s[62:63] offset:16
; __global__ void __launch_bounds__(512, 2) mega(Params P0) {
;     ...
;         else if (ph == 11) { const float* r3 = (const float*)(ws + WS_RSS3); const float* fw = P.in[23]; const f32x4* h3 = (const f32x4*)(ws + WS_H1);
;             const int nchunk = NTOK * DM / 4 / 1024; const int wv = bid * 8 + (tid >> 6), lane = tid & 63;
;             for (int ck = wv; ck < nchunk; ck += G * 8) { f32x4 v[16];
; #pragma unroll
;                 for (int j = 0; j < 16; ++j) v[j] = __builtin_nontemporal_load(h3 + (ck * 16 + j) * 64 + lane);
; #pragma unroll
;                 for (int j = 0; j < 16; ++j) { const int i = (ck * 16 + j) * 64 + lane; const int row = i >> 8, c4 = i & 255; const float rstd = rsqrtf(r3[row] * (1.0f / DM) + 1e-6f);
;                     __builtin_nontemporal_store(v[j] * rstd * *(const f32x4*)(fw + 4 * c4), (f32x4*)P.out + i); } } }
	global_store_dwordx4 v200, v[54:57], s[62:63] offset:512
	global_store_dwordx4 v200, v[50:53], s[62:63] offset:528
	s_add_u32 s62, s52, 0x90000
	s_addc_u32 s63, s53, 0
	v_pk_mul_f32 v[46:47], v[46:47], v[170:171] op_sel:[0,1] op_sel_hi:[1,1]
	v_pk_mul_f32 v[48:49], v[48:49], v[170:171] op_sel:[0,1] op_sel_hi:[1,1]
	v_pk_mul_f32 v[42:43], v[42:43], v[170:171] op_sel:[0,1] op_sel_hi:[1,1]
	v_pk_mul_f32 v[44:45], v[44:45], v[170:171] op_sel:[0,1] op_sel_hi:[1,1]
	v_pk_mul_f32 v[38:39], v[38:39], v[170:171] op_sel:[0,1] op_sel_hi:[1,1]
	v_pk_mul_f32 v[40:41], v[40:41], v[170:171] op_sel:[0,1] op_sel_hi:[1,1]
	v_pk_mul_f32 v[34:35], v[34:35], v[170:171] op_sel:[0,1] op_sel_hi:[1,1]
	v_pk_mul_f32 v[36:37], v[36:37], v[170:171] op_sel:[0,1] op_sel_hi:[1,1]
	v_pk_mul_f32 v[46:47], v[46:47], v[240:241]
	v_pk_mul_f32 v[48:49], v[48:49], v[242:243]
	v_pk_mul_f32 v[42:43], v[42:43], v[244:245]
	v_pk_mul_f32 v[44:45], v[44:45], v[246:247]
	v_pk_mul_f32 v[38:39], v[38:39], v[248:249]
	v_pk_mul_f32 v[40:41], v[40:41], v[250:251]
	v_pk_mul_f32 v[34:35], v[34:35], v[232:233]
	v_pk_mul_f32 v[36:37], v[36:37], v[234:235]
	global_store_dwordx4 v200, v[46:49], s[62:63]
	global_store_dwordx4 v200, v[42:45], s[62:63] offset:16
	global_store_dwordx4 v200, v[38:41], s[62:63] offset:512
	global_store_dwordx4 v200, v[34:37], s[62:63] offset:528
	s_add_u32 s62, s52, 0xa0000
	s_addc_u32 s63, s53, 0
	v_pk_mul_f32 v[30:31], v[30:31], v[172:173] op_sel_hi:[1,0]
	v_pk_mul_f32 v[32:33], v[32:33], v[172:173] op_sel_hi:[1,0]
	v_pk_mul_f32 v[26:27], v[26:27], v[172:173] op_sel_hi:[1,0]
	v_pk_mul_f32 v[28:29], v[28:29], v[172:173] op_sel_hi:[1,0]
	v_pk_mul_f32 v[22:23], v[22:23], v[172:173] op_sel_hi:[1,0]
	v_pk_mul_f32 v[24:25], v[24:25], v[172:173] op_sel_hi:[1,0]
	v_pk_mul_f32 v[18:19], v[18:19], v[172:173] op_sel_hi:[1,0]
	v_pk_mul_f32 v[20:21], v[20:21], v[172:173] op_sel_hi:[1,0]
	v_pk_mul_f32 v[30:31], v[30:31], v[240:241]
	v_pk_mul_f32 v[32:33], v[32:33], v[242:243]
	v_pk_mul_f32 v[26:27], v[26:27], v[244:245]
	v_pk_mul_f32 v[28:29], v[28:29], v[246:247]
	v_pk_mul_f32 v[22:23], v[22:23], v[248:249]
	v_pk_mul_f32 v[24:25], v[24:25], v[250:251]
	v_pk_mul_f32 v[18:19], v[18:19], v[232:233]
	v_pk_mul_f32 v[20:21], v[20:21], v[234:235]
	global_store_dwordx4 v200, v[30:33], s[62:63]
	global_store_dwordx4 v200, v[26:29], s[62:63] offset:16
	global_store_dwordx4 v200, v[22:25], s[62:63] offset:512
	global_store_dwordx4 v200, v[18:21], s[62:63] offset:528
	s_add_u32 s62, s52, 0xb0000
	s_addc_u32 s63, s53, 0
	v_pk_mul_f32 v[14:15], v[14:15], v[172:173] op_sel:[0,1] op_sel_hi:[1,1]
	v_pk_mul_f32 v[16:17], v[16:17], v[172:173] op_sel:[0,1] op_sel_hi:[1,1]
	v_pk_mul_f32 v[10:11], v[10:11], v[172:173] op_sel:[0,1] op_sel_hi:[1,1]
	v_pk_mul_f32 v[12:13], v[12:13], v[172:173] op_sel:[0,1] op_sel_hi:[1,1]
	v_pk_mul_f32 v[6:7], v[6:7], v[172:173] op_sel:[0,1] op_sel_hi:[1,1]
	v_pk_mul_f32 v[8:9], v[8:9], v[172:173] op_sel:[0,1] op_sel_hi:[1,1]
	v_pk_mul_f32 v[2:3], v[2:3], v[172:173] op_sel:[0,1] op_sel_hi:[1,1]
	v_pk_mul_f32 v[4:5], v[4:5], v[172:173] op_sel:[0,1] op_sel_hi:[1,1]
	v_pk_mul_f32 v[14:15], v[14:15], v[240:241]
	v_pk_mul_f32 v[16:17], v[16:17], v[242:243]
	v_pk_mul_f32 v[10:11], v[10:11], v[244:245]
	v_pk_mul_f32 v[12:13], v[12:13], v[246:247]
	v_pk_mul_f32 v[6:7], v[6:7], v[248:249]
	v_pk_mul_f32 v[8:9], v[8:9], v[250:251]
	v_pk_mul_f32 v[2:3], v[2:3], v[232:233]
	v_pk_mul_f32 v[4:5], v[4:5], v[234:235]
	global_store_dwordx4 v200, v[14:17], s[62:63]
	global_store_dwordx4 v200, v[10:13], s[62:63] offset:16
	global_store_dwordx4 v200, v[6:9], s[62:63] offset:512
	global_store_dwordx4 v200, v[2:5], s[62:63] offset:528
	s_mov_b64 s[2:3], 0
	s_branch .LBB0_766
